# v22 + phase-0 transpose tiles rebalanced: GEMV workgroups 15 tiles, the other 64 workgroups 27 tiles
# speedup vs baseline: 1.0331x; 1.0014x over previous
; DI void phase0(const Params& p, char* smem, int wv) {
;     ...
;     auto tr_desc = [&](int ti, const float*& src, u16*& dst, int& N, int& kt, int& nt) {
;       if (ti < N_TRIN) {
;         const int l = ti / 896, rem = ti % 896; kt = rem / 56; nt = rem % 56; N = INW;
;         src = p.w_in + (size_t)l * DM * INW; dst = p.wt_in + (size_t)l * INW * DM;
;       } else {
;         const int t2 = ti - N_TRIN;
;         const int l = t2 / 256, rem = t2 % 256; kt = rem / 16; nt = rem % 16; N = DM;
;         src = p.w_out + (size_t)l * DM * DM; dst = p.wt_out + (size_t)l * DM * DM;
;       }
;     };
;     const int row0 = tid >> 5, c4 = (tid & 31) * 4;
;     const int g = gridDim.x;
;     int ti = (blockIdx.x + g - (N_MOD % g)) % g;
;     f32x4 v[8];
;     const float* src; u16* dst; int N, kt, nt;
;     if (ti < N_TR) {
;       tr_desc(ti, src, dst, N, kt, nt);
.LBB0_581:
	v_readlane_b32 s0, v253, 1
	v_readlane_b32 s1, v253, 2
	s_load_dword s2, s[0:1], 0x0
	s_nop 0
	s_load_dword s0, s[0:1], 0x10
	s_waitcnt lgkmcnt(0)
	s_lshr_b32 s0, s0, 16
	s_cmp_lg_u32 s0, 0
	s_cselect_b64 s[0:1], -1, 0
	s_cmp_lg_u64 s[0:1], 0
	s_addc_u32 s10, s2, 0
	s_abs_i32 s0, s10
	v_cvt_f32_u32_e32 v0, s0
	s_sub_i32 s1, 0, s0
	v_rcp_iflag_f32_e32 v0, v0
	s_nop 0
	v_mul_f32_e32 v0, 0x4f7ffffe, v0
	v_cvt_u32_f32_e32 v0, v0
	s_nop 0
	v_readfirstlane_b32 s2, v0
	v_cvt_f32_u32_e32 v0, s10
	s_mul_i32 s1, s1, s2
	s_mul_hi_u32 s1, s2, s1
	s_add_i32 s2, s2, s1
	s_mul_hi_u32 s1, s2, 0xc0
	v_rcp_iflag_f32_e32 v0, v0
	s_mul_i32 s1, s1, s0
	s_sub_i32 s1, 0xc0, s1
	s_sub_i32 s2, s1, s0
	s_cmp_ge_u32 s1, s0
	v_mul_f32_e32 v0, 0x4f7ffffe, v0
	s_cselect_b32 s1, s2, s1
	v_cvt_u32_f32_e32 v0, v0
	s_sub_i32 s2, s1, s0
	s_cmp_ge_u32 s1, s0
	s_cselect_b32 s0, s2, s1
	v_readlane_b32 s1, v253, 0
	s_sub_i32 s0, s1, s0
	s_sub_i32 s1, 0, s10
	v_readfirstlane_b32 s2, v0
	s_mul_i32 s1, s1, s2
	s_mul_hi_u32 s1, s2, s1
	s_add_i32 s0, s0, s10
	s_add_i32 s2, s2, s1
	s_mul_hi_u32 s1, s0, s2
	s_mul_i32 s1, s1, s10
	s_sub_i32 s0, s0, s1
	s_sub_i32 s1, s0, s10
	s_cmp_ge_u32 s0, s10
	s_cselect_b32 s0, s1, s0
	s_sub_i32 s1, s0, s10
	s_cmp_ge_u32 s0, s10
	s_cselect_b32 s11, s1, s0
	s_movk_i32 s32, 0x11ff
	s_cmpk_lg_i32 s10, 0x100
	s_cbranch_scc1 .Ltb_done
	v_readlane_b32 s0, v253, 0
	s_cmpk_lt_u32 s0, 0xc0
	s_cbranch_scc1 .Ltb_g
	s_sub_i32 s11, s0, 0xc0
	s_movk_i32 s10, 0x40
	s_movk_i32 s32, 0x6bf
	s_branch .Ltb_done
.Ltb_g:
	s_add_i32 s11, s0, 0x6c0
	s_movk_i32 s10, 0xc0
.Ltb_done:
	s_cmp_le_i32 s11, s32
	s_cbranch_scc0 .LBB0_5
	s_cmpk_gt_i32 s11, 0xdff
	s_mov_b64 s[2:3], -1
	s_cbranch_scc0 .LBB0_584
	s_add_i32 s0, s11, 0xfffff200
	s_mov_b64 s[78:79], s[54:55]
	s_lshr_b32 s18, s0, 8
	s_mov_b64 s[76:77], s[52:53]
	s_mov_b64 s[74:75], s[50:51]
	s_mov_b64 s[72:73], s[48:49]
	s_mov_b64 s[70:71], s[46:47]
	s_mov_b64 s[68:69], s[44:45]
	s_mov_b64 s[66:67], s[42:43]
	s_mov_b64 s[64:65], s[40:41]
	v_readlane_b32 s36, v253, 21
	s_bfe_u32 s13, s11, 0x40004
	s_and_b32 s12, s11, 15
	s_lshl_b64 s[0:1], s[18:19], 24
	v_readlane_b32 s38, v253, 23
	v_readlane_b32 s39, v253, 24
	s_add_u32 s4, s38, s0
	v_readlane_b32 s46, v253, 31
	s_addc_u32 s5, s39, s1
	s_lshl_b64 s[0:1], s[18:19], 23
	v_readlane_b32 s40, v253, 25
	v_readlane_b32 s41, v253, 26
	v_readlane_b32 s42, v253, 27
	v_readlane_b32 s43, v253, 28
	v_readlane_b32 s44, v253, 29
	v_readlane_b32 s45, v253, 30
	v_readlane_b32 s47, v253, 32
	v_readlane_b32 s48, v253, 33
	v_readlane_b32 s49, v253, 34
	v_readlane_b32 s50, v253, 35
	v_readlane_b32 s51, v253, 36
	s_add_u32 s0, s46, s0
	s_addc_u32 s1, s47, s1
	s_mov_b64 s[40:41], s[64:65]
	v_readlane_b32 s37, v253, 22
	s_mov_b32 s18, 0x1e000
	s_mov_b64 s[42:43], s[66:67]
	s_mov_b64 s[44:45], s[68:69]
	s_mov_b64 s[46:47], s[70:71]
	s_mov_b64 s[48:49], s[72:73]
	s_mov_b64 s[50:51], s[74:75]
	s_mov_b64 s[52:53], s[76:77]
	s_mov_b64 s[54:55], s[78:79]
	s_mov_b64 s[2:3], 0

; DI void phase0(const Params& p, char* smem, int wv) {
;     ...
;     for (; ti < N_TR; ti += g) {
; #pragma unroll
;       for (int i = 0; i < 8; ++i) {
;         float* d = sf + (row0 + 16 * i) * 129 + c4;
;         d[0] = v[i][0]; d[1] = v[i][1]; d[2] = v[i][2]; d[3] = v[i][3];
;       }
;       __syncthreads();
;       u16* dcur = dst; const int ktc = kt, ntc = nt;
;       if (ti + g < N_TR) {
;         tr_desc(ti + g, src, dst, N, kt, nt);
; #pragma unroll
;         for (int i = 0; i < 8; ++i) v[i] = *(const f32x4*)(src + (size_t)(kt * 128 + row0 + 16 * i) * N + nt * 128 + c4);
;       }
.LBB0_589:
	v_add_u32_e32 v35, 0x2040, v39
	s_waitcnt vmcnt(11)
	ds_write2_b32 v39, v2, v3 offset1:1
	ds_write2_b32 v39, v4, v5 offset0:2 offset1:3
	s_waitcnt vmcnt(10)
	ds_write2_b32 v35, v6, v7 offset1:1
	v_add_u32_e32 v35, 0x2048, v39
	ds_write2_b32 v35, v8, v9 offset1:1
	v_add_u32_e32 v35, 0x4080, v39
	s_waitcnt vmcnt(9)
	ds_write2_b32 v35, v10, v11 offset1:1
	v_add_u32_e32 v35, 0x4088, v39
	ds_write2_b32 v35, v12, v13 offset1:1
	v_add_u32_e32 v35, 0x60c0, v39
	s_waitcnt vmcnt(8)
	ds_write2_b32 v35, v14, v15 offset1:1
	v_add_u32_e32 v35, 0x60c8, v39
	ds_write2_b32 v35, v16, v17 offset1:1
	v_add_u32_e32 v35, 0x8100, v39
	s_waitcnt vmcnt(7)
	ds_write2_b32 v35, v18, v19 offset1:1
	v_add_u32_e32 v35, 0x8108, v39
	ds_write2_b32 v35, v20, v21 offset1:1
	v_add_u32_e32 v35, 0xa140, v39
	s_waitcnt vmcnt(6)
	ds_write2_b32 v35, v22, v23 offset1:1
	v_add_u32_e32 v35, 0xa148, v39
	ds_write2_b32 v35, v24, v25 offset1:1
	v_add_u32_e32 v35, 0xc180, v39
	s_add_i32 s11, s11, s10
	s_waitcnt vmcnt(5)
	ds_write2_b32 v35, v26, v27 offset1:1
	v_add_u32_e32 v35, 0xc188, v39
	s_cmp_gt_i32 s11, s32
	ds_write2_b32 v35, v28, v29 offset1:1
	v_add_u32_e32 v35, 0xe1c0, v39
	s_cselect_b64 s[4:5], -1, 0
	s_waitcnt vmcnt(4)
	ds_write2_b32 v35, v30, v31 offset1:1
	v_add_u32_e32 v35, 0xe1c8, v39
	s_and_b64 vcc, exec, s[4:5]
	ds_write2_b32 v35, v32, v33 offset1:1
	s_waitcnt lgkmcnt(0)
	s_barrier
	s_cbranch_vccnz .LBB0_588
	s_cmpk_gt_i32 s11, 0xdff
	s_mov_b64 s[6:7], -1
	s_cbranch_scc0 .LBB0_592
	s_add_i32 s2, s11, 0xfffff200
	s_mov_b64 s[78:79], s[54:55]
	s_lshr_b32 s18, s2, 8
	s_mov_b64 s[76:77], s[52:53]
	s_mov_b64 s[74:75], s[50:51]
	s_mov_b64 s[72:73], s[48:49]
	s_mov_b64 s[70:71], s[46:47]
	s_mov_b64 s[68:69], s[44:45]
	s_mov_b64 s[66:67], s[42:43]
	s_mov_b64 s[64:65], s[40:41]
	v_readlane_b32 s36, v253, 21
	s_bfe_u32 s14, s11, 0x40004
	s_and_b32 s15, s11, 15
	s_lshl_b64 s[2:3], s[18:19], 24
	v_readlane_b32 s38, v253, 23
	v_readlane_b32 s39, v253, 24
	s_add_u32 s8, s38, s2
	v_readlane_b32 s46, v253, 31
	s_addc_u32 s9, s39, s3
	s_lshl_b64 s[2:3], s[18:19], 23
	v_readlane_b32 s40, v253, 25
	v_readlane_b32 s41, v253, 26
	v_readlane_b32 s42, v253, 27
	v_readlane_b32 s43, v253, 28
	v_readlane_b32 s44, v253, 29
	v_readlane_b32 s45, v253, 30
	v_readlane_b32 s47, v253, 32
	v_readlane_b32 s48, v253, 33
	v_readlane_b32 s49, v253, 34
	v_readlane_b32 s50, v253, 35
	v_readlane_b32 s51, v253, 36
	s_add_u32 s2, s46, s2
	s_addc_u32 s3, s47, s3
	s_mov_b64 s[40:41], s[64:65]
	v_readlane_b32 s37, v253, 22
	s_mov_b32 s18, 0x1e000
	s_mov_b64 s[42:43], s[66:67]
	s_mov_b64 s[44:45], s[68:69]
	s_mov_b64 s[46:47], s[70:71]
	s_mov_b64 s[48:49], s[72:73]
	s_mov_b64 s[50:51], s[74:75]
	s_mov_b64 s[52:53], s[76:77]
	s_mov_b64 s[54:55], s[78:79]
	s_mov_b64 s[6:7], 0
